# mask block hardened: 2 wait states between v_cmp vcc and v_cndmask (hazard row 18); otherwise identical to previous best
# baseline (speedup 1.0000x reference)
; __device__ __forceinline__ void attn_unit(KParams& P, int l, const AUnit& U, LAS unsigned char* lds) {
;     ...
;         if ((t + 1) * 64 > U.kvlen) {
;             const int kb0 = t * 64 + 8 * hi;
; #pragma unroll
;             for (int r = 0; r < 16; ++r) { const int kv = kb0 + 16 * (r >> 3) + (r & 7); if (kv >= U.kvlen) p0[r] = -INFINITY; if (kv + 32 >= U.kvlen) p1[r] = -INFINITY; }
;         }
.Lattn_noload_y:
	s_nop 7
	s_lshl_b32 s25, s20, 6
	s_add_i32 s28, s25, 64
	s_cmp_le_u32 s28, s70
	s_cbranch_scc1 .Lattn_nomask
	v_add_u32_e32 v208, s25, v164
	v_add_u32_e32 v209, 0, v208
	v_cmp_gt_u32_e32 vcc, s70, v209
	s_nop 1
	v_cndmask_b32_e32 v80, v225, v80, vcc
	v_add_u32_e32 v209, 32, v208
	v_cmp_gt_u32_e32 vcc, s70, v209
	s_nop 1
	v_cndmask_b32_e32 v64, v225, v64, vcc
	v_add_u32_e32 v209, 1, v208
	v_cmp_gt_u32_e32 vcc, s70, v209
	s_nop 1
	v_cndmask_b32_e32 v81, v225, v81, vcc
	v_add_u32_e32 v209, 33, v208
	v_cmp_gt_u32_e32 vcc, s70, v209
	s_nop 1
	v_cndmask_b32_e32 v65, v225, v65, vcc
	v_add_u32_e32 v209, 2, v208
	v_cmp_gt_u32_e32 vcc, s70, v209
	s_nop 1
	v_cndmask_b32_e32 v82, v225, v82, vcc
	v_add_u32_e32 v209, 34, v208
	v_cmp_gt_u32_e32 vcc, s70, v209
	s_nop 1
	v_cndmask_b32_e32 v66, v225, v66, vcc
	v_add_u32_e32 v209, 3, v208
	v_cmp_gt_u32_e32 vcc, s70, v209
	s_nop 1
	v_cndmask_b32_e32 v83, v225, v83, vcc
	v_add_u32_e32 v209, 35, v208
	v_cmp_gt_u32_e32 vcc, s70, v209
	s_nop 1
	v_cndmask_b32_e32 v67, v225, v67, vcc
	v_add_u32_e32 v209, 4, v208
	v_cmp_gt_u32_e32 vcc, s70, v209
	s_nop 1
	v_cndmask_b32_e32 v84, v225, v84, vcc
	v_add_u32_e32 v209, 36, v208
	v_cmp_gt_u32_e32 vcc, s70, v209
	s_nop 1
	v_cndmask_b32_e32 v68, v225, v68, vcc
	v_add_u32_e32 v209, 5, v208
	v_cmp_gt_u32_e32 vcc, s70, v209
	s_nop 1
	v_cndmask_b32_e32 v85, v225, v85, vcc
	v_add_u32_e32 v209, 37, v208
	v_cmp_gt_u32_e32 vcc, s70, v209
	s_nop 1
	v_cndmask_b32_e32 v69, v225, v69, vcc
	v_add_u32_e32 v209, 6, v208
	v_cmp_gt_u32_e32 vcc, s70, v209
	s_nop 1
	v_cndmask_b32_e32 v86, v225, v86, vcc
	v_add_u32_e32 v209, 38, v208
	v_cmp_gt_u32_e32 vcc, s70, v209
	s_nop 1
	v_cndmask_b32_e32 v70, v225, v70, vcc
	v_add_u32_e32 v209, 7, v208
	v_cmp_gt_u32_e32 vcc, s70, v209
	s_nop 1
	v_cndmask_b32_e32 v87, v225, v87, vcc
	v_add_u32_e32 v209, 39, v208
	v_cmp_gt_u32_e32 vcc, s70, v209
	s_nop 1
	v_cndmask_b32_e32 v71, v225, v71, vcc
	v_add_u32_e32 v209, 16, v208
	v_cmp_gt_u32_e32 vcc, s70, v209
	s_nop 1
	v_cndmask_b32_e32 v88, v225, v88, vcc
	v_add_u32_e32 v209, 48, v208
	v_cmp_gt_u32_e32 vcc, s70, v209
	s_nop 1
	v_cndmask_b32_e32 v72, v225, v72, vcc
	v_add_u32_e32 v209, 17, v208
	v_cmp_gt_u32_e32 vcc, s70, v209
	s_nop 1
	v_cndmask_b32_e32 v89, v225, v89, vcc
	v_add_u32_e32 v209, 49, v208
	v_cmp_gt_u32_e32 vcc, s70, v209
	s_nop 1
	v_cndmask_b32_e32 v73, v225, v73, vcc
	v_add_u32_e32 v209, 18, v208
	v_cmp_gt_u32_e32 vcc, s70, v209
	s_nop 1
	v_cndmask_b32_e32 v90, v225, v90, vcc
	v_add_u32_e32 v209, 50, v208
	v_cmp_gt_u32_e32 vcc, s70, v209
	s_nop 1
	v_cndmask_b32_e32 v74, v225, v74, vcc
	v_add_u32_e32 v209, 19, v208
	v_cmp_gt_u32_e32 vcc, s70, v209
	s_nop 1
	v_cndmask_b32_e32 v91, v225, v91, vcc
	v_add_u32_e32 v209, 51, v208
	v_cmp_gt_u32_e32 vcc, s70, v209
	s_nop 1
	v_cndmask_b32_e32 v75, v225, v75, vcc
	v_add_u32_e32 v209, 20, v208
	v_cmp_gt_u32_e32 vcc, s70, v209
	s_nop 1
	v_cndmask_b32_e32 v92, v225, v92, vcc
	v_add_u32_e32 v209, 52, v208
	v_cmp_gt_u32_e32 vcc, s70, v209
	s_nop 1
	v_cndmask_b32_e32 v76, v225, v76, vcc
	v_add_u32_e32 v209, 21, v208
	v_cmp_gt_u32_e32 vcc, s70, v209
	s_nop 1
	v_cndmask_b32_e32 v93, v225, v93, vcc
	v_add_u32_e32 v209, 53, v208
	v_cmp_gt_u32_e32 vcc, s70, v209
	s_nop 1
	v_cndmask_b32_e32 v77, v225, v77, vcc
	v_add_u32_e32 v209, 22, v208
	v_cmp_gt_u32_e32 vcc, s70, v209
	s_nop 1
	v_cndmask_b32_e32 v94, v225, v94, vcc
	v_add_u32_e32 v209, 54, v208
	v_cmp_gt_u32_e32 vcc, s70, v209
	s_nop 1
	v_cndmask_b32_e32 v78, v225, v78, vcc
	v_add_u32_e32 v209, 23, v208
	v_cmp_gt_u32_e32 vcc, s70, v209
	s_nop 1
	v_cndmask_b32_e32 v95, v225, v95, vcc
	v_add_u32_e32 v209, 55, v208
	v_cmp_gt_u32_e32 vcc, s70, v209
	s_nop 1
	v_cndmask_b32_e32 v79, v225, v79, vcc
